# grid barriers: L1 invalidate issued at arrival (overlaps the wait) instead of after release
# speedup vs baseline: 1.0134x; 1.0134x over previous
.LBB0_77:
	s_mov_b64 s[4:5], exec
	v_mbcnt_lo_u32_b32 v1, s4, 0
	v_mbcnt_hi_u32_b32 v1, s5, v1
	v_cmp_eq_u32_e32 vcc, 0, v1
	s_and_saveexec_b64 s[2:3], vcc
	s_cbranch_execz .LBB0_79
	s_bcnt1_i32_b64 s4, s[4:5]
	v_mov_b32_e32 v4, s4
	v_readlane_b32 s4, v253, 62
	v_mov_b32_e32 v3, 0
	v_readlane_b32 s5, v253, 63
	s_nop 4
	global_atomic_add v3, v3, v4, s[4:5] sc0
	buffer_inv sc1
.LBB0_79:
	s_or_b64 exec, exec, s[2:3]
	v_cvt_f32_u32_e32 v4, v2
	s_waitcnt vmcnt(1)
	v_readfirstlane_b32 s2, v3
	v_sub_u32_e32 v3, 0, v2
	v_rcp_iflag_f32_e32 v4, v4
	v_add_u32_e32 v5, s2, v1
	v_mul_f32_e32 v4, 0x4f7ffffe, v4
	v_cvt_u32_f32_e32 v4, v4
	v_mul_lo_u32 v1, v3, v4
	v_mul_hi_u32 v1, v4, v1
	v_add_u32_e32 v1, v4, v1
	v_mul_hi_u32 v1, v5, v1
	v_mul_lo_u32 v3, v1, v2
	v_sub_u32_e32 v3, v5, v3
	v_add_u32_e32 v4, 1, v1
	v_cmp_ge_u32_e32 vcc, v3, v2
	s_nop 1
	v_cndmask_b32_e32 v1, v1, v4, vcc
	v_sub_u32_e32 v4, v3, v2
	v_cndmask_b32_e32 v3, v3, v4, vcc
	v_add_u32_e32 v4, 1, v1
	v_cmp_ge_u32_e32 vcc, v3, v2
	v_add_u32_e32 v3, 1, v5
	s_nop 0
	v_cndmask_b32_e32 v1, v1, v4, vcc
	v_mul_lo_u32 v4, v2, v1
	v_add_u32_e32 v2, v4, v2
	v_cmp_ne_u32_e32 vcc, v3, v2
	s_and_saveexec_b64 s[2:3], vcc
	s_xor_b64 s[2:3], exec, s[2:3]
	s_cbranch_execz .LBB0_93
	s_waitcnt lgkmcnt(0)
	v_mov_b32_e32 v0, 0
	global_load_dword v2, v0, s[34:35] sc1
	s_waitcnt vmcnt(0)
	v_cmp_eq_u32_e32 vcc, v2, v1
	s_and_saveexec_b64 s[4:5], vcc
	s_cbranch_execz .LBB0_92
	s_mov_b32 s16, 1
	s_mov_b64 s[6:7], 0
	s_branch .LBB0_83

.LBB0_92:
	s_or_b64 exec, exec, s[4:5]
	s_waitcnt vmcnt(0)
	s_waitcnt vmcnt(0)

.LBB0_110:
	s_or_b64 exec, exec, s[2:3]
	s_mov_b64 s[2:3], exec
	v_mbcnt_lo_u32_b32 v0, s2, 0
	v_mbcnt_hi_u32_b32 v0, s3, v0
	v_cmp_eq_u32_e32 vcc, 0, v0
	s_waitcnt vmcnt(0)
	s_and_saveexec_b64 s[4:5], vcc
	s_cbranch_execz .LBB0_112
	s_bcnt1_i32_b64 s2, s[2:3]
	v_mov_b32_e32 v0, 0
	v_mov_b32_e32 v1, s2
	global_atomic_add v0, v1, s[34:35]
